# grid barrier: XCD leader issues its invalidate right after the L2 write-back instead of after the top-level wait
# baseline (speedup 1.0000x reference)
.LBB0_146:
	s_andn2_saveexec_b64 s[2:3], s[10:11]
	s_cbranch_execz .LBB0_166
	s_mov_b64 s[10:11], exec
	buffer_wbl2 sc1
	s_waitcnt lgkmcnt(0)
	s_waitcnt vmcnt(0)
	buffer_inv sc1
	v_mbcnt_lo_u32_b32 v1, s10, 0
	v_mbcnt_hi_u32_b32 v1, s11, v1
	v_cmp_eq_u32_e32 vcc, 0, v1
	s_and_saveexec_b64 s[12:13], vcc
	s_cbranch_execz .LBB0_149
	s_bcnt1_i32_b64 s2, s[10:11]
	v_mov_b32_e32 v2, 0x13000
	v_mov_b32_e32 v3, s2
	global_atomic_add v2, v2, v3, s[6:7] offset:1024 sc0

.LBB0_163:
	s_or_b64 exec, exec, s[6:7]
	s_mov_b64 s[6:7], exec
	v_mbcnt_lo_u32_b32 v0, s6, 0
	v_mbcnt_hi_u32_b32 v0, s7, v0
	v_cmp_eq_u32_e32 vcc, 0, v0
	s_waitcnt vmcnt(0)
	s_and_saveexec_b64 s[10:11], vcc
	s_cbranch_execz .LBB0_165
	s_bcnt1_i32_b64 s2, s[6:7]
	v_mov_b32_e32 v0, 0x2000
	v_mov_b32_e32 v1, s2
	global_atomic_add v0, v1, s[8:9] offset:1024

.LBB0_223:
	s_andn2_saveexec_b64 s[10:11], s[10:11]
	s_cbranch_execz .LBB0_243
	s_mov_b64 s[10:11], exec
	buffer_wbl2 sc1
	s_waitcnt lgkmcnt(0)
	s_waitcnt vmcnt(0)
	buffer_inv sc1
	v_mbcnt_lo_u32_b32 v1, s10, 0
	v_mbcnt_hi_u32_b32 v1, s11, v1
	v_cmp_eq_u32_e32 vcc, 0, v1
	s_and_saveexec_b64 s[12:13], vcc
	s_cbranch_execz .LBB0_226
	s_bcnt1_i32_b64 s10, s[10:11]
	v_mov_b32_e32 v3, s10
	v_mov_b32_e32 v4, 0x13000
	global_atomic_add v3, v4, v3, s[6:7] offset:1024 sc0

.LBB0_240:
	s_or_b64 exec, exec, s[6:7]
	s_mov_b64 s[6:7], exec
	v_mbcnt_lo_u32_b32 v1, s6, 0
	v_mbcnt_hi_u32_b32 v1, s7, v1
	v_cmp_eq_u32_e32 vcc, 0, v1
	s_waitcnt vmcnt(0)
	s_and_saveexec_b64 s[10:11], vcc
	s_cbranch_execz .LBB0_242
	s_bcnt1_i32_b64 s6, s[6:7]
	v_mov_b32_e32 v1, s6
	v_mov_b32_e32 v2, 0x2000
	global_atomic_add v2, v1, s[8:9] offset:1024

.LBB0_1567:
	s_mov_b64 s[10:11], exec
	buffer_wbl2 sc1
	s_waitcnt lgkmcnt(0)
	s_waitcnt vmcnt(0)
	buffer_inv sc1
	v_mbcnt_lo_u32_b32 v1, s10, 0
	v_mbcnt_hi_u32_b32 v1, s11, v1
	v_cmp_eq_u32_e32 vcc, 0, v1
	s_and_saveexec_b64 s[12:13], vcc
	s_cbranch_execz .LBB0_1569
	s_bcnt1_i32_b64 s10, s[10:11]
	v_mov_b32_e32 v3, s10
	v_mov_b32_e32 v4, 0x13000
	global_atomic_add v3, v4, v3, s[6:7] offset:1024 sc0

.LBB0_1583:
	s_or_b64 exec, exec, s[6:7]
	s_mov_b64 s[6:7], exec
	v_mbcnt_lo_u32_b32 v1, s6, 0
	v_mbcnt_hi_u32_b32 v1, s7, v1
	v_cmp_eq_u32_e32 vcc, 0, v1
	s_waitcnt vmcnt(0)
	s_and_saveexec_b64 s[10:11], vcc
	s_cbranch_execnz .LBB0_1584
	s_getpc_b64 s[98:99]
